# m20 + non-temporal hint on the final RMSNorm output stores
# speedup vs baseline: 1.0025x; 1.0025x over previous
; __device__ __forceinline__ float bf_lo(unsigned u) { return __uint_as_float(u << 16); }
; __device__ __forceinline__ float bf_hi(unsigned u) { return __uint_as_float(u & 0xffff0000u); }
; __device__ __forceinline__ float rstd_of(const unsigned long long* ssq, int row) { return rsqrtf((float)ssq[row] * (1.0f / (SSQ_SCALE * 1024.0f)) + EPS); }
; __global__ void __launch_bounds__(512, 2) mk_fwd(Args a) {
;     ...
;     if (IN(8)) {
;         const float* gf = a.in[22];
;         for (int orow0 = gw * 4; orow0 < NOUT_ROWS; orow0 += NGW * 4) {
;             u32x4 hv[4][2]; float rs[4];
; #pragma unroll
;             for (int i = 0; i < 4; ++i) { const int row = orow0 + i;
;                 rs[i] = rstd_of(SSQ3, row);
; #pragma unroll
;                 for (int j = 0; j < 2; ++j) hv[i][j] = *(const u32x4*)(H + (size_t)row * D + (j * 64 + lane) * 8); }
; #pragma unroll
;             for (int j = 0; j < 2; ++j) { const int col = (j * 64 + lane) * 8; const f32x4 g0 = *(const f32x4*)(gf + col), g1 = *(const f32x4*)(gf + col + 4);
; #pragma unroll
;                 for (int i = 0; i < 4; ++i) { const u32x4 h4 = hv[i][j]; const float r = rs[i];
;                     f32x4 o0, o1; o0.x = bf_lo(h4.x) * r * g0.x; o0.y = bf_hi(h4.x) * r * g0.y; o0.z = bf_lo(h4.y) * r * g0.z; o0.w = bf_hi(h4.y) * r * g0.w;
;                     o1.x = bf_lo(h4.z) * r * g1.x; o1.y = bf_hi(h4.z) * r * g1.y; o1.z = bf_lo(h4.w) * r * g1.z; o1.w = bf_hi(h4.w) * r * g1.w;
;                     float* op = a.out + (size_t)(orow0 + i) * D + col; *(f32x4*)op = o0; *(f32x4*)(op + 4) = o1; } }
;         }
.Lp8_noload:
	v_add_co_u32_e32 v54, vcc, 0x1000, v50
	s_nop 1
	v_addc_co_u32_e32 v55, vcc, 0, v51, vcc
	v_add_co_u32_e32 v56, vcc, 0x2000, v50
	s_nop 1
	v_addc_co_u32_e32 v57, vcc, 0, v51, vcc
	v_add_co_u32_e32 v58, vcc, 0x3000, v50
	s_nop 1
	v_addc_co_u32_e32 v59, vcc, 0, v51, vcc
	v_ffbh_u32_e32 v0, v177
	v_ffbh_u32_e32 v4, v179
	v_min_u32_e32 v2, 32, v0
	v_min_u32_e32 v6, 32, v4
	v_lshlrev_b64 v[0:1], v2, v[176:177]
	v_lshlrev_b64 v[4:5], v6, v[178:179]
	v_min_u32_e32 v0, 1, v0
	v_min_u32_e32 v4, 1, v4
	v_or_b32_e32 v0, v1, v0
	v_or_b32_e32 v4, v5, v4
	v_cvt_f32_u32_e32 v0, v0
	v_cvt_f32_u32_e32 v4, v4
	v_sub_u32_e32 v1, 32, v2
	v_sub_u32_e32 v5, 32, v6
	v_ldexp_f32 v0, v0, v1
	v_ldexp_f32 v4, v4, v5
	v_fmamk_f32 v0, v0, 0x30800000, v68
	v_fmamk_f32 v4, v4, 0x30800000, v68
	v_mul_f32_e32 v1, 0x4b800000, v0
	v_mul_f32_e32 v5, 0x4b800000, v4
	v_cmp_gt_f32_e32 vcc, s7, v0
	v_cmp_gt_f32_e64 s[2:3], s7, v4
	s_nop 0
	v_cndmask_b32_e32 v0, v0, v1, vcc
	v_cndmask_b32_e64 v4, v4, v5, s[2:3]
	v_rsq_f32_e32 v0, v0
	v_rsq_f32_e32 v4, v4
	v_mul_f32_e32 v1, 0x45800000, v0
	v_mul_f32_e32 v5, 0x45800000, v4
	v_cndmask_b32_e32 v60, v0, v1, vcc
	v_cndmask_b32_e64 v62, v4, v5, s[2:3]
	v_ffbh_u32_e32 v0, v181
	v_ffbh_u32_e32 v4, v183
	v_min_u32_e32 v2, 32, v0
	v_min_u32_e32 v6, 32, v4
	v_lshlrev_b64 v[0:1], v2, v[180:181]
	v_lshlrev_b64 v[4:5], v6, v[182:183]
	v_min_u32_e32 v0, 1, v0
	v_min_u32_e32 v4, 1, v4
	v_or_b32_e32 v0, v1, v0
	v_or_b32_e32 v4, v5, v4
	v_cvt_f32_u32_e32 v0, v0
	v_cvt_f32_u32_e32 v4, v4
	v_sub_u32_e32 v1, 32, v2
	v_sub_u32_e32 v5, 32, v6
	v_ldexp_f32 v0, v0, v1
	v_ldexp_f32 v4, v4, v5
	v_fmamk_f32 v0, v0, 0x30800000, v68
	v_fmamk_f32 v4, v4, 0x30800000, v68
	v_mul_f32_e32 v1, 0x4b800000, v0
	v_mul_f32_e32 v5, 0x4b800000, v4
	v_cmp_gt_f32_e32 vcc, s7, v0
	v_cmp_gt_f32_e64 s[2:3], s7, v4
	s_nop 0
	v_cndmask_b32_e32 v0, v0, v1, vcc
	v_cndmask_b32_e64 v4, v4, v5, s[2:3]
	v_rsq_f32_e32 v0, v0
	v_rsq_f32_e32 v4, v4
	v_mul_f32_e32 v1, 0x45800000, v0
	v_mul_f32_e32 v5, 0x45800000, v4
	v_cndmask_b32_e32 v64, v0, v1, vcc
	v_cndmask_b32_e64 v66, v4, v5, s[2:3]
	v_lshlrev_b32_e32 v16, 16, v144
	v_and_b32_e32 v17, 0xffff0000, v144
	v_lshlrev_b32_e32 v18, 16, v145
	v_and_b32_e32 v19, 0xffff0000, v145
	v_lshlrev_b32_e32 v20, 16, v146
	v_and_b32_e32 v21, 0xffff0000, v146
	v_lshlrev_b32_e32 v22, 16, v147
	v_and_b32_e32 v23, 0xffff0000, v147
	v_pk_mul_f32 v[16:17], v[60:61], v[16:17] op_sel_hi:[0,1]
	v_pk_mul_f32 v[18:19], v[60:61], v[18:19] op_sel_hi:[0,1]
	v_pk_mul_f32 v[20:21], v[60:61], v[20:21] op_sel_hi:[0,1]
	v_pk_mul_f32 v[22:23], v[60:61], v[22:23] op_sel_hi:[0,1]
	v_pk_mul_f32 v[32:33], v[88:89], v[16:17]
	v_pk_mul_f32 v[34:35], v[90:91], v[18:19]
	v_pk_mul_f32 v[36:37], v[92:93], v[20:21]
	v_pk_mul_f32 v[38:39], v[94:95], v[22:23]
	global_store_dwordx4 v[50:51], v[32:35], off nt
	global_store_dwordx4 v[50:51], v[36:39], off offset:1024 nt
	v_lshlrev_b32_e32 v16, 16, v148
	v_and_b32_e32 v17, 0xffff0000, v148
	v_lshlrev_b32_e32 v18, 16, v149
	v_and_b32_e32 v19, 0xffff0000, v149
	v_lshlrev_b32_e32 v20, 16, v150
	v_and_b32_e32 v21, 0xffff0000, v150
	v_lshlrev_b32_e32 v22, 16, v151
	v_and_b32_e32 v23, 0xffff0000, v151
	v_pk_mul_f32 v[16:17], v[60:61], v[16:17] op_sel_hi:[0,1]
	v_pk_mul_f32 v[18:19], v[60:61], v[18:19] op_sel_hi:[0,1]
	v_pk_mul_f32 v[20:21], v[60:61], v[20:21] op_sel_hi:[0,1]
	v_pk_mul_f32 v[22:23], v[60:61], v[22:23] op_sel_hi:[0,1]
	v_pk_mul_f32 v[40:41], v[96:97], v[16:17]
	v_pk_mul_f32 v[42:43], v[98:99], v[18:19]
	v_pk_mul_f32 v[44:45], v[100:101], v[20:21]
	v_pk_mul_f32 v[46:47], v[102:103], v[22:23]
	global_store_dwordx4 v[50:51], v[40:43], off offset:2048 nt
	global_store_dwordx4 v[50:51], v[44:47], off offset:3072 nt
	v_lshlrev_b32_e32 v16, 16, v152
	v_and_b32_e32 v17, 0xffff0000, v152
	v_lshlrev_b32_e32 v18, 16, v153
	v_and_b32_e32 v19, 0xffff0000, v153
	v_lshlrev_b32_e32 v20, 16, v154
	v_and_b32_e32 v21, 0xffff0000, v154
	v_lshlrev_b32_e32 v22, 16, v155
	v_and_b32_e32 v23, 0xffff0000, v155
	v_pk_mul_f32 v[16:17], v[62:63], v[16:17] op_sel_hi:[0,1]
	v_pk_mul_f32 v[18:19], v[62:63], v[18:19] op_sel_hi:[0,1]
	v_pk_mul_f32 v[20:21], v[62:63], v[20:21] op_sel_hi:[0,1]
	v_pk_mul_f32 v[22:23], v[62:63], v[22:23] op_sel_hi:[0,1]
	v_pk_mul_f32 v[32:33], v[88:89], v[16:17]
	v_pk_mul_f32 v[34:35], v[90:91], v[18:19]
; __device__ __forceinline__ float bf_lo(unsigned u) { return __uint_as_float(u << 16); }
; __device__ __forceinline__ float bf_hi(unsigned u) { return __uint_as_float(u & 0xffff0000u); }
; __global__ void __launch_bounds__(512, 2) mk_fwd(Args a) {
;     ...
;             for (int j = 0; j < 2; ++j) { const int col = (j * 64 + lane) * 8; const f32x4 g0 = *(const f32x4*)(gf + col), g1 = *(const f32x4*)(gf + col + 4);
; #pragma unroll
;                 for (int i = 0; i < 4; ++i) { const u32x4 h4 = hv[i][j]; const float r = rs[i];
;                     f32x4 o0, o1; o0.x = bf_lo(h4.x) * r * g0.x; o0.y = bf_hi(h4.x) * r * g0.y; o0.z = bf_lo(h4.y) * r * g0.z; o0.w = bf_hi(h4.y) * r * g0.w;
;                     o1.x = bf_lo(h4.z) * r * g1.x; o1.y = bf_hi(h4.z) * r * g1.y; o1.z = bf_lo(h4.w) * r * g1.z; o1.w = bf_hi(h4.w) * r * g1.w;
;                     float* op = a.out + (size_t)(orow0 + i) * D + col; *(f32x4*)op = o0; *(f32x4*)(op + 4) = o1; } }
;         }
	v_pk_mul_f32 v[36:37], v[92:93], v[20:21]
	v_pk_mul_f32 v[38:39], v[94:95], v[22:23]
	global_store_dwordx4 v[54:55], v[32:35], off nt
	global_store_dwordx4 v[54:55], v[36:39], off offset:1024 nt
	v_lshlrev_b32_e32 v16, 16, v156
	v_and_b32_e32 v17, 0xffff0000, v156
	v_lshlrev_b32_e32 v18, 16, v157
	v_and_b32_e32 v19, 0xffff0000, v157
	v_lshlrev_b32_e32 v20, 16, v158
	v_and_b32_e32 v21, 0xffff0000, v158
	v_lshlrev_b32_e32 v22, 16, v159
	v_and_b32_e32 v23, 0xffff0000, v159
	v_pk_mul_f32 v[16:17], v[62:63], v[16:17] op_sel_hi:[0,1]
	v_pk_mul_f32 v[18:19], v[62:63], v[18:19] op_sel_hi:[0,1]
	v_pk_mul_f32 v[20:21], v[62:63], v[20:21] op_sel_hi:[0,1]
	v_pk_mul_f32 v[22:23], v[62:63], v[22:23] op_sel_hi:[0,1]
	v_pk_mul_f32 v[40:41], v[96:97], v[16:17]
	v_pk_mul_f32 v[42:43], v[98:99], v[18:19]
	v_pk_mul_f32 v[44:45], v[100:101], v[20:21]
	v_pk_mul_f32 v[46:47], v[102:103], v[22:23]
	global_store_dwordx4 v[54:55], v[40:43], off offset:2048 nt
	global_store_dwordx4 v[54:55], v[44:47], off offset:3072 nt
	v_lshlrev_b32_e32 v16, 16, v160
	v_and_b32_e32 v17, 0xffff0000, v160
	v_lshlrev_b32_e32 v18, 16, v161
	v_and_b32_e32 v19, 0xffff0000, v161
	v_lshlrev_b32_e32 v20, 16, v162
	v_and_b32_e32 v21, 0xffff0000, v162
	v_lshlrev_b32_e32 v22, 16, v163
	v_and_b32_e32 v23, 0xffff0000, v163
	v_pk_mul_f32 v[16:17], v[64:65], v[16:17] op_sel_hi:[0,1]
	v_pk_mul_f32 v[18:19], v[64:65], v[18:19] op_sel_hi:[0,1]
	v_pk_mul_f32 v[20:21], v[64:65], v[20:21] op_sel_hi:[0,1]
	v_pk_mul_f32 v[22:23], v[64:65], v[22:23] op_sel_hi:[0,1]
	v_pk_mul_f32 v[32:33], v[88:89], v[16:17]
	v_pk_mul_f32 v[34:35], v[90:91], v[18:19]
	v_pk_mul_f32 v[36:37], v[92:93], v[20:21]
	v_pk_mul_f32 v[38:39], v[94:95], v[22:23]
	global_store_dwordx4 v[56:57], v[32:35], off nt
	global_store_dwordx4 v[56:57], v[36:39], off offset:1024 nt
	v_lshlrev_b32_e32 v16, 16, v164
	v_and_b32_e32 v17, 0xffff0000, v164
	v_lshlrev_b32_e32 v18, 16, v165
	v_and_b32_e32 v19, 0xffff0000, v165
	v_lshlrev_b32_e32 v20, 16, v166
	v_and_b32_e32 v21, 0xffff0000, v166
	v_lshlrev_b32_e32 v22, 16, v167
	v_and_b32_e32 v23, 0xffff0000, v167
	v_pk_mul_f32 v[16:17], v[64:65], v[16:17] op_sel_hi:[0,1]
	v_pk_mul_f32 v[18:19], v[64:65], v[18:19] op_sel_hi:[0,1]
	v_pk_mul_f32 v[20:21], v[64:65], v[20:21] op_sel_hi:[0,1]
	v_pk_mul_f32 v[22:23], v[64:65], v[22:23] op_sel_hi:[0,1]
	v_pk_mul_f32 v[40:41], v[96:97], v[16:17]
	v_pk_mul_f32 v[42:43], v[98:99], v[18:19]
	v_pk_mul_f32 v[44:45], v[100:101], v[20:21]
	v_pk_mul_f32 v[46:47], v[102:103], v[22:23]
	global_store_dwordx4 v[56:57], v[40:43], off offset:2048 nt
	global_store_dwordx4 v[56:57], v[44:47], off offset:3072 nt
	v_lshlrev_b32_e32 v16, 16, v168
	v_and_b32_e32 v17, 0xffff0000, v168
	v_lshlrev_b32_e32 v18, 16, v169
	v_and_b32_e32 v19, 0xffff0000, v169
	v_lshlrev_b32_e32 v20, 16, v170
	v_and_b32_e32 v21, 0xffff0000, v170
	v_lshlrev_b32_e32 v22, 16, v171
	v_and_b32_e32 v23, 0xffff0000, v171
	v_pk_mul_f32 v[16:17], v[66:67], v[16:17] op_sel_hi:[0,1]
	v_pk_mul_f32 v[18:19], v[66:67], v[18:19] op_sel_hi:[0,1]
	v_pk_mul_f32 v[20:21], v[66:67], v[20:21] op_sel_hi:[0,1]
	v_pk_mul_f32 v[22:23], v[66:67], v[22:23] op_sel_hi:[0,1]
	v_pk_mul_f32 v[32:33], v[88:89], v[16:17]
	v_pk_mul_f32 v[34:35], v[90:91], v[18:19]
	v_pk_mul_f32 v[36:37], v[92:93], v[20:21]
	v_pk_mul_f32 v[38:39], v[94:95], v[22:23]
	global_store_dwordx4 v[58:59], v[32:35], off nt
	global_store_dwordx4 v[58:59], v[36:39], off offset:1024 nt
	v_lshlrev_b32_e32 v16, 16, v172
	v_and_b32_e32 v17, 0xffff0000, v172
	v_lshlrev_b32_e32 v18, 16, v173
	v_and_b32_e32 v19, 0xffff0000, v173
	v_lshlrev_b32_e32 v20, 16, v174
	v_and_b32_e32 v21, 0xffff0000, v174
	v_lshlrev_b32_e32 v22, 16, v175
	v_and_b32_e32 v23, 0xffff0000, v175
	v_pk_mul_f32 v[16:17], v[66:67], v[16:17] op_sel_hi:[0,1]
	v_pk_mul_f32 v[18:19], v[66:67], v[18:19] op_sel_hi:[0,1]
	v_pk_mul_f32 v[20:21], v[66:67], v[20:21] op_sel_hi:[0,1]
	v_pk_mul_f32 v[22:23], v[66:67], v[22:23] op_sel_hi:[0,1]
	v_pk_mul_f32 v[40:41], v[96:97], v[16:17]
	v_pk_mul_f32 v[42:43], v[98:99], v[18:19]
	v_pk_mul_f32 v[44:45], v[100:101], v[20:21]
	v_pk_mul_f32 v[46:47], v[102:103], v[22:23]
	global_store_dwordx4 v[58:59], v[40:43], off offset:2048 nt
	global_store_dwordx4 v[58:59], v[44:47], off offset:3072 nt
	v_lshl_add_u64 v[50:51], v[50:51], 0, s[14:15]
	s_cmp_lt_i32 s6, 0x18000
	s_cbranch_scc1 .Lp8_top
